# P0 mod item: SiLU(c) staging loop issues its 8 loads up front (SGPR base + 32-bit offsets) instead of 8 dependent load-wait rounds
# speedup vs baseline: 1.0090x; 1.0090x over previous
; DI void mod_item(const Params& p, int item, char* smem) {
;     ...
;   __syncthreads();
;   for (int i = t; i < 4 * 512; i += 256) { float v = c[(i >> 9) * 2048 + kbase + (i & 511)]; cact[i] = v / (1.f + __expf(-v)); }
;   __syncthreads();
;   const int cq = t & 15, kl = t >> 4, c0 = cgi * 64;
;   float acc[4][4];
; #pragma unroll
;   for (int b = 0; b < 4; ++b)
; #pragma unroll
;     for (int j = 0; j < 4; ++j) acc[b][j] = 0.f;
;   const float* wp = W + (size_t)(kbase + kl) * 12288 + c0 + cq * 4;
.LBB0_173:
	s_lshl_b32 s5, s4, 2
	v_add_u32_e32 v160, s5, v11
	v_add_u32_e32 v161, 0x2000, v160
	v_add_u32_e32 v162, 0x4000, v160
	v_add_u32_e32 v163, 0x6000, v160
	global_load_dword v170, v160, s[58:59]
	global_load_dword v171, v160, s[58:59] offset:1024
	global_load_dword v172, v161, s[58:59]
	global_load_dword v173, v161, s[58:59] offset:1024
	global_load_dword v174, v162, s[58:59]
	global_load_dword v175, v162, s[58:59] offset:1024
	global_load_dword v176, v163, s[58:59]
	global_load_dword v177, v163, s[58:59] offset:1024
	s_waitcnt vmcnt(7)
	v_mul_f32_e32 v180, 0xbfb8aa3b, v170
	v_exp_f32_e32 v181, v180
	s_nop 0
	v_add_f32_e32 v182, 1.0, v181
	v_div_scale_f32 v181, s[44:45], v182, v182, v170
	v_rcp_f32_e32 v183, v181
	v_div_scale_f32 v184, vcc, v170, v182, v170
	v_fma_f32 v185, -v181, v183, 1.0
	v_fmac_f32_e32 v183, v185, v183
	v_mul_f32_e32 v185, v184, v183
	v_fma_f32 v186, -v181, v185, v184
	v_fmac_f32_e32 v185, v186, v183
	v_fma_f32 v181, -v181, v185, v184
	v_div_fmas_f32 v181, v181, v183, v185
	v_div_fixup_f32 v170, v181, v182, v170
	ds_write_b32 v11, v170 offset:16
	s_waitcnt vmcnt(6)
	v_mul_f32_e32 v180, 0xbfb8aa3b, v171
	v_exp_f32_e32 v181, v180
	s_nop 0
	v_add_f32_e32 v182, 1.0, v181
	v_div_scale_f32 v181, s[44:45], v182, v182, v171
	v_rcp_f32_e32 v183, v181
	v_div_scale_f32 v184, vcc, v171, v182, v171
	v_fma_f32 v185, -v181, v183, 1.0
	v_fmac_f32_e32 v183, v185, v183
	v_mul_f32_e32 v185, v184, v183
	v_fma_f32 v186, -v181, v185, v184
	v_fmac_f32_e32 v185, v186, v183
	v_fma_f32 v181, -v181, v185, v184
	v_div_fmas_f32 v181, v181, v183, v185
	v_div_fixup_f32 v171, v181, v182, v171
	ds_write_b32 v11, v171 offset:1040
	s_waitcnt vmcnt(5)
	v_mul_f32_e32 v180, 0xbfb8aa3b, v172
	v_exp_f32_e32 v181, v180
	s_nop 0
	v_add_f32_e32 v182, 1.0, v181
	v_div_scale_f32 v181, s[44:45], v182, v182, v172
	v_rcp_f32_e32 v183, v181
	v_div_scale_f32 v184, vcc, v172, v182, v172
	v_fma_f32 v185, -v181, v183, 1.0
	v_fmac_f32_e32 v183, v185, v183
	v_mul_f32_e32 v185, v184, v183
	v_fma_f32 v186, -v181, v185, v184
	v_fmac_f32_e32 v185, v186, v183
	v_fma_f32 v181, -v181, v185, v184
	v_div_fmas_f32 v181, v181, v183, v185
	v_div_fixup_f32 v172, v181, v182, v172
	ds_write_b32 v11, v172 offset:2064
	s_waitcnt vmcnt(4)
	v_mul_f32_e32 v180, 0xbfb8aa3b, v173
	v_exp_f32_e32 v181, v180
	s_nop 0
	v_add_f32_e32 v182, 1.0, v181
	v_div_scale_f32 v181, s[44:45], v182, v182, v173
	v_rcp_f32_e32 v183, v181
	v_div_scale_f32 v184, vcc, v173, v182, v173
	v_fma_f32 v185, -v181, v183, 1.0
	v_fmac_f32_e32 v183, v185, v183
	v_mul_f32_e32 v185, v184, v183
	v_fma_f32 v186, -v181, v185, v184
	v_fmac_f32_e32 v185, v186, v183
	v_fma_f32 v181, -v181, v185, v184
	v_div_fmas_f32 v181, v181, v183, v185
	v_div_fixup_f32 v173, v181, v182, v173
	ds_write_b32 v11, v173 offset:3088
	s_waitcnt vmcnt(3)
	v_mul_f32_e32 v180, 0xbfb8aa3b, v174
	v_exp_f32_e32 v181, v180
	s_nop 0
	v_add_f32_e32 v182, 1.0, v181
	v_div_scale_f32 v181, s[44:45], v182, v182, v174
	v_rcp_f32_e32 v183, v181
	v_div_scale_f32 v184, vcc, v174, v182, v174
	v_fma_f32 v185, -v181, v183, 1.0
	v_fmac_f32_e32 v183, v185, v183
	v_mul_f32_e32 v185, v184, v183
	v_fma_f32 v186, -v181, v185, v184
	v_fmac_f32_e32 v185, v186, v183
	v_fma_f32 v181, -v181, v185, v184
	v_div_fmas_f32 v181, v181, v183, v185
	v_div_fixup_f32 v174, v181, v182, v174
	ds_write_b32 v11, v174 offset:4112
	s_waitcnt vmcnt(2)
	v_mul_f32_e32 v180, 0xbfb8aa3b, v175
	v_exp_f32_e32 v181, v180
	s_nop 0
	v_add_f32_e32 v182, 1.0, v181
	v_div_scale_f32 v181, s[44:45], v182, v182, v175
	v_rcp_f32_e32 v183, v181
	v_div_scale_f32 v184, vcc, v175, v182, v175
	v_fma_f32 v185, -v181, v183, 1.0
	v_fmac_f32_e32 v183, v185, v183
	v_mul_f32_e32 v185, v184, v183
	v_fma_f32 v186, -v181, v185, v184
	v_fmac_f32_e32 v185, v186, v183
	v_fma_f32 v181, -v181, v185, v184
	v_div_fmas_f32 v181, v181, v183, v185
	v_div_fixup_f32 v175, v181, v182, v175
	ds_write_b32 v11, v175 offset:5136
	s_waitcnt vmcnt(1)
	v_mul_f32_e32 v180, 0xbfb8aa3b, v176
	v_exp_f32_e32 v181, v180
	s_nop 0
	v_add_f32_e32 v182, 1.0, v181
	v_div_scale_f32 v181, s[44:45], v182, v182, v176
	v_rcp_f32_e32 v183, v181
	v_div_scale_f32 v184, vcc, v176, v182, v176
	v_fma_f32 v185, -v181, v183, 1.0
	v_fmac_f32_e32 v183, v185, v183
	v_mul_f32_e32 v185, v184, v183
	v_fma_f32 v186, -v181, v185, v184
	v_fmac_f32_e32 v185, v186, v183
	v_fma_f32 v181, -v181, v185, v184
	v_div_fmas_f32 v181, v181, v183, v185
	v_div_fixup_f32 v176, v181, v182, v176
	ds_write_b32 v11, v176 offset:6160
	s_waitcnt vmcnt(0)
	v_mul_f32_e32 v180, 0xbfb8aa3b, v177
	v_exp_f32_e32 v181, v180
	s_nop 0
	v_add_f32_e32 v182, 1.0, v181
	v_div_scale_f32 v181, s[44:45], v182, v182, v177
	v_rcp_f32_e32 v183, v181
	v_div_scale_f32 v184, vcc, v177, v182, v177
	v_fma_f32 v185, -v181, v183, 1.0
	v_fmac_f32_e32 v183, v185, v183
	v_mul_f32_e32 v185, v184, v183
	v_fma_f32 v186, -v181, v185, v184
	v_fmac_f32_e32 v185, v186, v183
	v_fma_f32 v181, -v181, v185, v184
	v_div_fmas_f32 v181, v181, v183, v185
	v_div_fixup_f32 v177, v181, v182, v177
	ds_write_b32 v11, v177 offset:7184
	s_or_b64 exec, exec, s[2:3]
	s_mul_i32 s2, s6, 0xc0
	s_sub_i32 s2, s37, s2
	s_lshl_b32 s2, s2, 6
	v_or_b32_e32 v4, s4, v1
	v_mov_b64_e32 v[2:3], s[60:61]
	s_mov_b32 s3, 0xc000
	v_mad_i64_i32 v[2:3], s[4:5], v4, s3, v[2:3]
	s_ashr_i32 s3, s2, 31
	v_lshl_add_u64 v[2:3], s[2:3], 2, v[2:3]
	v_mov_b32_e32 v31, v13
	v_mov_b32_e32 v4, 0
	v_lshl_add_u64 v[2:3], v[2:3], 0, v[30:31]
	s_mov_b64 s[4:5], 0
	v_mov_b32_e32 v12, v60
	v_mov_b32_e32 v5, v4
	v_mov_b32_e32 v6, v4
	v_mov_b32_e32 v7, v4
	v_mov_b32_e32 v8, v4
	v_mov_b32_e32 v9, v4
	v_mov_b32_e32 v34, v4
	v_mov_b32_e32 v35, v4
	v_mov_b32_e32 v36, v4
	v_mov_b32_e32 v37, v4
	v_mov_b32_e32 v38, v4
	v_mov_b32_e32 v39, v4
	v_mov_b32_e32 v40, v4
	v_mov_b32_e32 v41, v4
	v_mov_b32_e32 v42, v4
	v_mov_b32_e32 v43, v4
	s_waitcnt lgkmcnt(0)
	s_barrier
